# attn_sample QK and PV inner loops: all LDS reads of an iteration issued together with one counted lgkmcnt wait, FMA order unchanged
# speedup vs baseline: 1.0070x; 1.0070x over previous
.LBB0_531:
	v_add_u32_e32 v11, s14, v9
	v_add_u32_e32 v11, 0x10c20, v11
	v_add_u32_e32 v13, s14, v12
	ds_read_b128 v[146:149], v11
	ds_read_b128 v[150:153], v11 offset:16
	ds_read2_b32 v[154:155], v13 offset1:1
	ds_read2_b32 v[156:157], v13 offset0:2 offset1:3
	ds_read2_b32 v[158:159], v13 offset0:4 offset1:5
	ds_read2_b32 v[160:161], v13 offset0:6 offset1:7
	ds_read_b128 v[182:185], v11 offset:32
	ds_read_b128 v[186:189], v11 offset:48
	ds_read2_b32 v[190:191], v13 offset0:8 offset1:9
	ds_read2_b32 v[192:193], v13 offset0:10 offset1:11
	ds_read2_b32 v[194:195], v13 offset0:12 offset1:13
	ds_read2_b32 v[196:197], v13 offset0:14 offset1:15
	s_add_i32 s14, s14, 64
	s_cmpk_eq_i32 s14, 0x100
	s_waitcnt lgkmcnt(6)
	v_fmac_f32_e32 v10, v146, v154
	v_fmac_f32_e32 v10, v147, v155
	v_fmac_f32_e32 v10, v148, v156
	v_fmac_f32_e32 v10, v149, v157
	v_fmac_f32_e32 v10, v150, v158
	v_fmac_f32_e32 v10, v151, v159
	v_fmac_f32_e32 v10, v152, v160
	v_fmac_f32_e32 v10, v153, v161
	s_waitcnt lgkmcnt(0)
	v_fmac_f32_e32 v10, v182, v190
	v_fmac_f32_e32 v10, v183, v191
	v_fmac_f32_e32 v10, v184, v192
	v_fmac_f32_e32 v10, v185, v193
	v_fmac_f32_e32 v10, v186, v194
	v_fmac_f32_e32 v10, v187, v195
	v_fmac_f32_e32 v10, v188, v196
	v_fmac_f32_e32 v10, v189, v197
	s_cbranch_scc0 .LBB0_531
	v_and_b32_e32 v9, 3, v5
	v_add_u32_e32 v9, s11, v9
	v_cvt_f32_ubyte0_e32 v9, v9
	v_mul_f32_e32 v11, -0.5, v9
	s_mov_b32 s14, 0xc2fc0000
	v_cmp_gt_f32_e32 vcc, s14, v11
	v_cvt_f32_u32_e32 v169, v7
	v_not_b32_e32 v7, 63
	v_cndmask_b32_e32 v11, 0, v227, vcc
	v_fmac_f32_e32 v11, -0.5, v9
	v_exp_f32_e32 v9, v11
	v_cndmask_b32_e32 v7, 0, v7, vcc
	v_ldexp_f32 v11, v9, v7
	v_pk_mul_f32 v[10:11], v[10:11], v[168:169]
	s_nop 0
	v_sub_f32_e32 v9, v10, v11
	s_branch .LBB0_528

.LBB0_544:
	v_add_u32_e32 v12, 0, v3
	v_add_u32_e32 v6, 0x11c20, v12
	v_add_u32_e32 v13, 0, v5
	v_add_u32_e32 v14, 0x400, v13
	v_add_u32_e32 v7, 0x800, v13
	ds_read_b128 v[146:149], v6
	ds_read_b128 v[150:153], v6 offset:16
	ds_read_b128 v[154:157], v6 offset:32
	ds_read2_b32 v[158:159], v13 offset1:65
	ds_read2_b32 v[160:161], v13 offset0:130 offset1:195
	ds_read2_b32 v[162:163], v14 offset0:4 offset1:69
	ds_read2_b32 v[164:165], v14 offset0:134 offset1:199
	ds_read2_b32 v[182:183], v7 offset0:8 offset1:73
	ds_read2_b32 v[184:185], v7 offset0:138 offset1:203
	s_add_i32 s6, s6, -12
	v_add_u32_e32 v5, 0xc30, v5
	v_add_u32_e32 v3, 48, v3
	s_cmp_lg_u32 s6, 0
	s_waitcnt lgkmcnt(0)
	v_fmac_f32_e32 v0, v146, v158
	v_fmac_f32_e32 v0, v147, v159
	v_fmac_f32_e32 v0, v148, v160
	v_fmac_f32_e32 v0, v149, v161
	v_fmac_f32_e32 v0, v150, v162
	v_fmac_f32_e32 v0, v151, v163
	v_fmac_f32_e32 v0, v152, v164
	v_fmac_f32_e32 v0, v153, v165
	v_fmac_f32_e32 v0, v154, v182
	v_fmac_f32_e32 v0, v155, v183
	v_fmac_f32_e32 v0, v156, v184
	v_fmac_f32_e32 v0, v157, v185
	s_cbranch_scc1 .LBB0_544
	v_cvt_pk_bf16_f32 v5, v0, v1
	v_ashrrev_i32_e32 v0, 8, v34
	v_and_b32_e32 v3, 0xc0, v34
	v_add_u32_e32 v0, s13, v0
	v_or_b32_e32 v3, s12, v3
	v_mov_b64_e32 v[6:7], s[88:89]
	v_mad_i64_i32 v[6:7], s[6:7], v0, s66, v[6:7]
	v_lshlrev_b32_e32 v0, 1, v3
	v_lshl_add_u64 v[6:7], v[6:7], 0, v[0:1]
	v_mov_b32_e32 v3, v1
	v_lshl_add_u64 v[6:7], v[6:7], 0, v[2:3]
	v_add_co_u32_e32 v6, vcc, 0x2000, v6
	s_movk_i32 s6, 0x1ff
	s_nop 0
	v_addc_co_u32_e32 v7, vcc, 0, v7, vcc
	v_add_u32_e32 v0, 0x200, v34
	v_cmp_lt_i32_e32 vcc, s6, v34
	s_or_b64 s[0:1], vcc, s[0:1]
	v_mov_b32_e32 v34, v0
	flat_store_short v[6:7], v5 offset:3104
	s_andn2_b64 exec, exec, s[0:1]
	s_cbranch_execnz .LBB0_543
